# M2 balance: the first-round a2 units are given to the half-block chains that have one fewer attention unit
# speedup vs baseline: 1.0046x; 1.0046x over previous
; DI void phase_m2(const Params& p, int l, int bid, int nb, h16* lds) {
;     ...
;   const int nA = conv_total(l) - 2560;
;   const int nB = (l + 1 < 4) ? 2560 : 0;
;   const int total = 32 + 136 + 2048 + 3072 + nA + nB;
;   if (l & 1) moe_reset(p, bid, nb);
;   const int ustart = (bid < 32) ? bid : bid;
;   const int ustep = (bid < 32) ? total : (nb - 32);
;   for (int u = ustart; u < total; u += ustep) {
.LBB0_892:
	s_and_b64 s[2:3], exec, s[2:3]
	s_movk_i32 s2, 0x2700
	s_cselect_b32 s91, s2, 0x5880
	v_readlane_b32 s2, v255, 30
	v_readlane_b32 s4, v255, 32
	v_readlane_b32 s3, v255, 31
	s_add_i32 s2, s4, 1
	v_readlane_b32 s5, v255, 33
	v_writelane_b32 v255, s2, 30
	s_cmp_lg_u32 s4, 3
	s_nop 0
	v_writelane_b32 v255, s3, 31
	s_cselect_b64 s[2:3], -1, 0
	v_writelane_b32 v255, s2, 36
	s_cmp_eq_u32 s4, 3
	s_nop 0
	v_writelane_b32 v255, s3, 37
	s_movk_i32 s2, 0xaa8
	s_cselect_b32 s2, s2, 0x14a8
	s_add_i32 s90, s91, s2
	v_cmp_gt_i32_e32 vcc, s90, v1
	s_and_saveexec_b64 s[64:65], vcc
	s_cbranch_execz .LBB0_1028
	v_readlane_b32 s16, v255, 32
	v_readlane_b32 s68, v255, 30
	v_readlane_b32 s2, v254, 31
	v_readlane_b32 s17, v255, 33
	v_readlane_b32 s69, v255, 31
	v_mov_b32_e32 v2, s2
	s_lshr_b32 s2, s68, 1
	s_mov_b32 s17, s69
	s_lshr_b32 s4, s16, 1
	v_readlane_b32 s36, v252, 11
	s_addk_i32 s91, 0xf600
	s_lshl_b32 s92, s16, 3
	s_mul_hi_u32 s6, s68, 0x2420000
	s_mul_i32 s7, s68, 0x2420000
	s_mul_i32 s66, s2, 0xb00000
	s_lshl_b32 s93, s2, 3
	s_lshl_b64 s[2:3], s[68:69], 22
	s_lshl_b32 s94, s4, 3
	s_mul_i32 s68, s4, 0xb00000
	s_lshl_b64 s[4:5], s[16:17], 22
	v_readlane_b32 s38, v252, 13
	v_readlane_b32 s48, v252, 23
	v_readlane_b32 s49, v252, 24
	v_readlane_b32 s50, v252, 25
	v_readlane_b32 s51, v252, 26
	v_readlane_b32 s39, v252, 14
	s_add_u32 s70, s38, s7
	v_readlane_b32 s48, v252, 43
	v_readlane_b32 s40, v252, 15
	v_readlane_b32 s41, v252, 16
	v_readlane_b32 s42, v252, 17
	v_readlane_b32 s43, v252, 18
	v_readlane_b32 s44, v252, 19
	v_readlane_b32 s45, v252, 20
	v_readlane_b32 s46, v252, 21
	v_readlane_b32 s47, v252, 22
	s_addc_u32 s71, s39, s6
	v_readlane_b32 s49, v252, 44
	v_readlane_b32 s50, v252, 45
	v_readlane_b32 s51, v252, 46
	v_readlane_b32 s52, v252, 47
	v_readlane_b32 s53, v252, 48
	v_readlane_b32 s54, v252, 49
	v_readlane_b32 s55, v252, 50
	v_readlane_b32 s56, v252, 51
	v_readlane_b32 s57, v252, 52
	s_add_u32 s72, s56, s66
	v_readlane_b32 s40, v252, 27
	s_addc_u32 s73, s57, 0
	v_readlane_b32 s50, v252, 37
	v_readlane_b32 s51, v252, 38
	s_add_u32 s74, s50, s2
	s_addc_u32 s75, s51, s3
	s_add_u32 s76, s56, s68
	s_addc_u32 s77, s57, 0
	s_add_u32 s78, s50, s4
	v_mov_b32_e32 v3, s90
	v_cmp_gt_i32_e32 vcc, 32, v1
	s_mul_hi_u32 s8, s16, 0x2420000
	v_writelane_b32 v255, s16, 32
	s_mul_i32 s9, s16, 0x2420000
	s_addc_u32 s79, s51, s5
	v_cndmask_b32_e32 v161, v2, v3, vcc
	s_add_u32 s80, s38, s9
	s_mov_b32 s67, s69
	v_writelane_b32 v255, s17, 33
	s_addc_u32 s81, s39, s8
	v_lshlrev_b32_e32 v162, 3, v1
	v_lshlrev_b32_e32 v163, 3, v161
	v_lshlrev_b32_e32 v164, 10, v1
	v_lshlrev_b32_e32 v165, 10, v161
	v_lshrrev_b32_e32 v162, 1, v181
	v_and_b32_e32 v163, 1, v181
	v_mov_b32_e32 v1, v181
	v_mov_b32_e32 v161, 0x1c0
	v_add_u32_e32 v215, 32, v162
	v_cmp_eq_u32_e32 vcc, 1, v163
	v_cndmask_b32_e32 v215, v162, v215, vcc
	v_mov_b32_e32 v165, s90
	v_cmp_gt_u32_e32 vcc, 32, v162
	v_cndmask_b32_e32 v1, v1, v215, vcc
	v_cndmask_b32_e32 v161, v161, v165, vcc
	v_lshlrev_b32_e32 v164, 10, v1
	v_mov_b32_e32 v162, v1
	v_subrev_u32_e32 v163, 64, v181
	v_add_u32_e32 v215, 0x130, v181
	v_cmp_gt_u32_e32 vcc, 0x68, v163
	v_cndmask_b32_e32 v1, v1, v215, vcc
	v_subrev_u32_e32 v163, 0x170, v181
	v_subrev_u32_e32 v215, 0x130, v181
	v_cmp_gt_u32_e32 vcc, 0x68, v163
	v_cndmask_b32_e32 v1, v1, v215, vcc
	s_mov_b64 s[82:83], 0
	v_readlane_b32 s37, v252, 12
	v_readlane_b32 s58, v252, 53
	v_readlane_b32 s59, v252, 54
	v_readlane_b32 s60, v252, 55
	v_readlane_b32 s61, v252, 56
	v_readlane_b32 s62, v252, 57
	v_readlane_b32 s63, v252, 58
	v_readlane_b32 s41, v252, 28
	v_readlane_b32 s42, v252, 29
	v_readlane_b32 s43, v252, 30
	v_readlane_b32 s44, v252, 31
	v_readlane_b32 s45, v252, 32
	v_readlane_b32 s46, v252, 33
	v_readlane_b32 s47, v252, 34
	v_readlane_b32 s48, v252, 35
	v_readlane_b32 s49, v252, 36
	v_readlane_b32 s52, v252, 39
	v_readlane_b32 s53, v252, 40
	v_readlane_b32 s54, v252, 41
	v_readlane_b32 s55, v252, 42
	s_branch .LBB0_897

; DI void phase_m2(const Params& p, int l, int bid, int nb, h16* lds) {
;     ...
;   for (int u = ustart; u < total; u += ustep) {
.LBB0_896:
	s_or_b64 exec, exec, s[4:5]
	v_add_u32_e32 v162, v162, v161
	v_mov_b32_e32 v1, v162
	v_mov_b32_e32 v215, s90
	v_cmp_le_u32_e32 vcc, 0xa8, v1
	s_mov_b64 s[36:37], vcc
	v_cmp_eq_u32_e32 vcc, 32, v161
	s_and_b64 vcc, vcc, s[36:37]
	v_cndmask_b32_e32 v1, v1, v215, vcc
	v_cmp_le_i32_e32 vcc, s90, v1
	s_or_b64 s[82:83], vcc, s[82:83]
	s_andn2_b64 exec, exec, s[82:83]
	s_cbranch_execz .LBB0_1028
